# W_b^T stored chunk-swizzled; both P4 tile loops read B through the map (compiler K-loops kept, only B address math replaced)
# speedup vs baseline: 1.0190x; 1.0032x over previous
.Ltr_p_d2:
	s_lshr_b32 s6, s5, 5
	s_and_b32 s7, s5, 31
	s_mov_b32 s12, 0x2000
	s_movk_i32 s13, 31
	s_mul_i32 s8, s6, 0x80000
	s_lshl_b32 s9, s7, 8
	s_add_u32 s8, s8, s9
	s_add_u32 s10, s34, s8
	s_addc_u32 s11, s35, 0
	s_lshl_b32 s8, s7, 18
	s_add_u32 s8, s8, 0x18288000
	s_add_u32 s14, s94, s8
	s_addc_u32 s15, s95, 0
	s_branch .Ltr_p_end

.LBB0_622:
	v_mov_b32_e32 v6, v204
	s_lshl_b32 s6, s22, 12
	v_add_u32_e32 v4, 0x100, v6
	v_lshlrev_b32_e32 v2, 4, v6
	v_ashrrev_i32_e32 v176, 4, v6
	v_ashrrev_i32_e32 v177, 4, v4
	v_lshl_add_u64 v[0:1], v[164:165], 0, s[6:7]
	v_and_b32_e32 v96, 0xf0, v2
	v_mul_lo_u32 v2, v176, s50
	v_mul_lo_u32 v4, v177, s50
	v_lshl_add_u64 v[0:1], v[0:1], 0, v[96:97]
	v_ashrrev_i32_e32 v3, 31, v2
	v_ashrrev_i32_e32 v5, 31, v4
	v_lshl_add_u64 v[2:3], v[2:3], 1, v[0:1]
	v_lshl_add_u64 v[4:5], v[4:5], 1, v[0:1]
	global_load_dwordx4 v[68:71], v[2:3], off
	global_load_dwordx4 v[64:67], v[4:5], off
	v_add_u32_e32 v2, 0x200, v6
	v_add_u32_e32 v4, 0x300, v6
	v_ashrrev_i32_e32 v178, 4, v2
	v_ashrrev_i32_e32 v179, 4, v4
	v_mul_lo_u32 v2, v178, s50
	v_mul_lo_u32 v4, v179, s50
	v_ashrrev_i32_e32 v3, 31, v2
	v_ashrrev_i32_e32 v5, 31, v4
	v_lshl_add_u64 v[2:3], v[2:3], 1, v[0:1]
	v_lshl_add_u64 v[4:5], v[4:5], 1, v[0:1]
	global_load_dwordx4 v[76:79], v[2:3], off
	global_load_dwordx4 v[72:75], v[4:5], off
	v_add_u32_e32 v2, 0x400, v6
	v_add_u32_e32 v4, 0x500, v6
	v_ashrrev_i32_e32 v180, 4, v2
	v_ashrrev_i32_e32 v181, 4, v4
	v_mul_lo_u32 v2, v180, s50
	v_mul_lo_u32 v4, v181, s50
	v_ashrrev_i32_e32 v3, 31, v2
	v_ashrrev_i32_e32 v5, 31, v4
	v_lshl_add_u64 v[2:3], v[2:3], 1, v[0:1]
	v_lshl_add_u64 v[4:5], v[4:5], 1, v[0:1]
	global_load_dwordx4 v[84:87], v[2:3], off
	global_load_dwordx4 v[80:83], v[4:5], off
	v_add_u32_e32 v2, 0x600, v6
	v_add_u32_e32 v4, 0x700, v6
	v_ashrrev_i32_e32 v182, 4, v2
	v_ashrrev_i32_e32 v183, 4, v4
	v_mul_lo_u32 v2, v182, s50
	v_mul_lo_u32 v4, v183, s50
	v_ashrrev_i32_e32 v3, 31, v2
	v_ashrrev_i32_e32 v5, 31, v4
	s_lshl_b32 s26, s22, 11
	v_lshl_add_u64 v[2:3], v[2:3], 1, v[0:1]
	v_lshl_add_u64 v[0:1], v[4:5], 1, v[0:1]
	v_mov_b32_e32 v4, v204
	s_cmp_eq_u32 s22, 1
	global_load_dwordx4 v[92:95], v[2:3], off
	global_load_dwordx4 v[88:91], v[0:1], off
	s_cselect_b32 s6, s49, 0x600
	v_bfe_u32 v2, v4, 4, 2
	s_cmp_eq_u32 s22, 0
	v_ashrrev_i32_e32 v3, 6, v4
	v_bitop3_b32 v2, v2, v4, 3 bitop3:0x78
	v_lshlrev_b32_e32 v7, 9, v4
	s_cselect_b32 s6, 0, s6
	v_lshlrev_b32_e32 v2, 3, v2
	v_lshlrev_b32_e32 v6, 16, v3
	v_and_b32_e32 v7, 0x7800, v7
	s_cselect_b32 s55, 32, 16
	s_lshl_b32 s6, s6, 1
	v_or3_b32 v2, v7, v6, v2
	s_add_u32 s28, s53, s6
	v_lshl_add_u32 v184, v3, 11, 32
	v_ashrrev_i32_e32 v3, 31, v2
	v_lshl_add_u64 v[0:1], v[166:167], 0, s[6:7]
	s_addc_u32 s29, s54, 0
	v_lshlrev_b64 v[2:3], 1, v[2:3]
	v_lshl_add_u64 v[168:169], v[0:1], 0, v[2:3]
	v_lshl_add_u64 v[170:171], s[28:29], 0, v[2:3]
	s_mov_b32 s76, s6
	s_add_u32 s77, s6, 0x80
	s_sub_u32 s80, s28, s6
	s_subb_u32 s81, s29, 0
	v_lshl_add_u64 v[210:211], s[80:81], 0, v[2:3]
	v_lshl_add_u64 v[212:213], v[210:211], 0, s[14:15]
	v_bfe_u32 v214, v204, 2, 4
	v_lshlrev_b32_e32 v214, 7, v214
	v_or_b32_e32 v215, 0x800, v214
	v_mov_b32_e32 v217, 0
	v_readfirstlane_b32 s6, v184
	v_add_u32_e32 v2, 0x400, v184
	v_add_u32_e32 v6, 0x2000, v184
	s_mov_b32 m0, s6
	v_readfirstlane_b32 s6, v2
	global_load_lds_dwordx4 v[168:169], off
	v_lshl_add_u64 v[0:1], v[168:169], 0, s[14:15]
	s_mov_b32 m0, s6
	v_readfirstlane_b32 s6, v6
	v_add_u32_e32 v2, 0x2400, v184
	global_load_lds_dwordx4 v[0:1], off
	s_mov_b32 m0, s6
	v_readfirstlane_b32 s6, v2
	v_add_u32_e32 v2, 0x4000, v184
	v_xor_b32_e32 v216, s76, v214
	v_lshl_add_u64 v[0:1], v[210:211], 0, v[216:217]
	global_load_lds_dwordx4 v[0:1], off
	v_xor_b32_e32 v216, s76, v215
	v_lshl_add_u64 v[0:1], v[212:213], 0, v[216:217]
	s_mov_b32 m0, s6
	v_readfirstlane_b32 s6, v2
	v_add_u32_e32 v2, 0x4400, v184
	global_load_lds_dwordx4 v[0:1], off
	v_lshl_add_u64 v[0:1], v[168:169], 0, 64
	s_mov_b32 m0, s6
	v_readfirstlane_b32 s6, v2
	v_add_u32_e32 v2, 0x6000, v184
	global_load_lds_dwordx4 v[0:1], off
	v_lshl_add_u64 v[0:1], v[168:169], 0, s[16:17]
	s_mov_b32 m0, s6
	v_readfirstlane_b32 s6, v2
	v_add_u32_e32 v2, 0x6400, v184
	global_load_lds_dwordx4 v[0:1], off
	v_xor_b32_e32 v216, s76, v214
	v_add_u32_e32 v216, 64, v216
	v_lshl_add_u64 v[0:1], v[210:211], 0, v[216:217]
	s_mov_b32 m0, s6
	v_readfirstlane_b32 s6, v2
	v_add_u32_e32 v2, 0x8000, v184
	global_load_lds_dwordx4 v[0:1], off
	v_xor_b32_e32 v216, s76, v215
	v_add_u32_e32 v216, 64, v216
	v_lshl_add_u64 v[0:1], v[212:213], 0, v[216:217]
	s_mov_b32 m0, s6
	v_readfirstlane_b32 s6, v2
	v_add_u32_e32 v2, 0x8400, v184
	global_load_lds_dwordx4 v[0:1], off
	v_lshl_add_u64 v[0:1], v[168:169], 0, s[18:19]
	s_mov_b32 m0, s6
	v_readfirstlane_b32 s6, v2
	v_add_u32_e32 v2, 0xa000, v184
	global_load_lds_dwordx4 v[0:1], off
	v_lshl_add_u64 v[0:1], v[168:169], 0, s[20:21]
	s_mov_b32 m0, s6
	v_readfirstlane_b32 s6, v2
	v_add_u32_e32 v2, 0xa400, v184
	global_load_lds_dwordx4 v[0:1], off
	v_xor_b32_e32 v216, s77, v214
	v_lshl_add_u64 v[0:1], v[210:211], 0, v[216:217]
	s_mov_b32 m0, s6
	v_readfirstlane_b32 s6, v2
	global_load_lds_dwordx4 v[0:1], off
	v_xor_b32_e32 v216, s77, v215
	v_lshl_add_u64 v[0:1], v[212:213], 0, v[216:217]
	s_mov_b32 m0, s6
	v_and_b32_e32 v5, 31, v4
	global_load_lds_dwordx4 v[0:1], off
	v_lshrrev_b32_e32 v3, 1, v4
	v_bfe_u32 v0, v4, 5, 1
	v_lshrrev_b32_e32 v1, 2, v4
	v_bfe_u32 v2, v4, 2, 2
	v_and_or_b32 v3, v3, s51, v5
	v_lshlrev_b32_e32 v185, 6, v3
	v_lshlrev_b32_e32 v3, 6, v4
	v_bitop3_b32 v1, v0, v1, 3 bitop3:0x78
	v_bitop3_b32 v0, v0, v2, 2 bitop3:0x36
	s_mov_b32 s27, s7
	s_mov_b32 s60, 3
	v_and_b32_e32 v186, 0x17c0, v3
	v_lshlrev_b32_e32 v187, 4, v1
	v_lshlrev_b32_e32 v188, 4, v0
	s_add_i32 s61, s55, -1
	s_movk_i32 s6, 0x60
	s_mov_b32 s64, 0
	v_mov_b32_e32 v0, 0
	v_mov_b32_e32 v1, v175
	v_mov_b32_e32 v2, v175
	v_mov_b32_e32 v3, v175
	v_mov_b32_e32 v4, v175
	v_mov_b32_e32 v5, v175
	v_mov_b32_e32 v6, v175
	v_mov_b32_e32 v7, v175
	v_mov_b32_e32 v8, v175
	v_mov_b32_e32 v9, v175
	v_mov_b32_e32 v10, v175
	v_mov_b32_e32 v11, v175
	v_mov_b32_e32 v12, v175
	v_mov_b32_e32 v13, v175
	v_mov_b32_e32 v14, v175
	v_mov_b32_e32 v15, v175
	v_mov_b32_e32 v16, 0
	v_mov_b32_e32 v17, v175
	v_mov_b32_e32 v18, v175
	v_mov_b32_e32 v19, v175
	v_mov_b32_e32 v20, v175
	v_mov_b32_e32 v21, v175
	v_mov_b32_e32 v22, v175
	v_mov_b32_e32 v23, v175
	v_mov_b32_e32 v24, v175
	v_mov_b32_e32 v25, v175
	v_mov_b32_e32 v26, v175
	v_mov_b32_e32 v27, v175
	v_mov_b32_e32 v28, v175
	v_mov_b32_e32 v29, v175
	v_mov_b32_e32 v30, v175
	v_mov_b32_e32 v31, v175
	v_mov_b32_e32 v32, 0
	v_mov_b32_e32 v33, v175
	v_mov_b32_e32 v34, v175
	v_mov_b32_e32 v35, v175
	v_mov_b32_e32 v36, v175
	v_mov_b32_e32 v37, v175
	v_mov_b32_e32 v38, v175
	v_mov_b32_e32 v39, v175
	v_mov_b32_e32 v40, v175
	v_mov_b32_e32 v41, v175
	v_mov_b32_e32 v42, v175
	v_mov_b32_e32 v43, v175
	v_mov_b32_e32 v44, v175
	v_mov_b32_e32 v45, v175
	v_mov_b32_e32 v46, v175
	v_mov_b32_e32 v47, v175
	v_mov_b32_e32 v48, 0
	v_mov_b32_e32 v49, v175
	v_mov_b32_e32 v50, v175
	v_mov_b32_e32 v51, v175
	v_mov_b32_e32 v52, v175
	v_mov_b32_e32 v53, v175
	v_mov_b32_e32 v54, v175
	v_mov_b32_e32 v55, v175
	v_mov_b32_e32 v56, v175
	v_mov_b32_e32 v57, v175
	v_mov_b32_e32 v58, v175
	v_mov_b32_e32 v59, v175
	v_mov_b32_e32 v60, v175
	v_mov_b32_e32 v61, v175
	v_mov_b32_e32 v62, v175
	v_mov_b32_e32 v63, v175
	s_branch .LBB0_624

.LBB0_634:
	s_andn2_b64 vcc, exec, s[28:29]
	s_cbranch_vccnz .LBB0_623
	s_lshl_b32 s65, s64, 14
	s_lshl_b64 s[28:29], s[6:7], 1
	s_and_b32 s78, s28, 0xffffff80
	s_add_u32 s78, s78, s76
	s_and_b32 s79, s28, 64
	s_add_i32 s66, s65, 0xffffc000
	s_cmp_lg_u32 s64, 0
	s_cselect_b32 s66, s66, 0xc000
	v_add_u32_e32 v189, s66, v184
	v_add_u32_e32 v192, 0x400, v189
	v_readfirstlane_b32 s66, v189
	v_lshl_add_u64 v[190:191], v[168:169], 0, s[28:29]
	s_mov_b32 m0, s66
	v_readfirstlane_b32 s66, v192
	global_load_lds_dwordx4 v[190:191], off
	v_lshl_add_u64 v[190:191], v[190:191], 0, s[14:15]
	s_mov_b32 m0, s66
	v_add_u32_e32 v192, 0x2000, v189
	global_load_lds_dwordx4 v[190:191], off
	v_xor_b32_e32 v216, s78, v214
	v_add_u32_e32 v216, s79, v216
	v_lshl_add_u64 v[190:191], v[210:211], 0, v[216:217]
	v_readfirstlane_b32 s28, v192
	v_add_u32_e32 v189, 0x2400, v189
	s_mov_b32 m0, s28
	v_readfirstlane_b32 s28, v189
	global_load_lds_dwordx4 v[190:191], off
	v_xor_b32_e32 v216, s78, v215
	v_add_u32_e32 v216, s79, v216
	v_lshl_add_u64 v[190:191], v[212:213], 0, v[216:217]
	s_mov_b32 m0, s28
	s_nop 0
	global_load_lds_dwordx4 v[190:191], off
	s_branch .LBB0_623

.LBB0_644:
	v_mov_b32_e32 v6, v204
	s_lshl_b32 s20, s45, 11
	s_lshl_b32 s6, s45, 12
	s_add_u32 s24, s48, s6
	v_add_u32_e32 v4, 0x100, v6
	v_lshlrev_b32_e32 v0, 4, v6
	v_ashrrev_i32_e32 v87, 4, v6
	v_ashrrev_i32_e32 v88, 4, v4
	s_addc_u32 s25, s49, 0
	v_and_b32_e32 v48, 0xf0, v0
	v_mul_lo_u32 v2, v87, s40
	v_mul_lo_u32 v4, v88, s40
	v_lshl_add_u64 v[0:1], s[24:25], 0, v[48:49]
	v_ashrrev_i32_e32 v3, 31, v2
	v_ashrrev_i32_e32 v5, 31, v4
	v_lshl_add_u64 v[2:3], v[2:3], 1, v[0:1]
	v_lshl_add_u64 v[4:5], v[4:5], 1, v[0:1]
	global_load_dwordx4 v[36:39], v[2:3], off
	global_load_dwordx4 v[32:35], v[4:5], off
	v_add_u32_e32 v2, 0x200, v6
	v_add_u32_e32 v4, 0x300, v6
	v_ashrrev_i32_e32 v89, 4, v2
	v_ashrrev_i32_e32 v90, 4, v4
	v_mul_lo_u32 v2, v89, s40
	v_mul_lo_u32 v4, v90, s40
	s_cmp_eq_u32 s45, 1
	v_ashrrev_i32_e32 v3, 31, v2
	v_ashrrev_i32_e32 v5, 31, v4
	s_cselect_b32 s6, s35, 0x600
	s_cmp_eq_u32 s45, 0
	v_lshl_add_u64 v[2:3], v[2:3], 1, v[0:1]
	v_lshl_add_u64 v[0:1], v[4:5], 1, v[0:1]
	v_mov_b32_e32 v4, v204
	global_load_dwordx4 v[44:47], v[2:3], off
	global_load_dwordx4 v[40:43], v[0:1], off
	s_cselect_b32 s6, 0, s6
	s_cselect_b32 s54, 32, 16
	v_bfe_u32 v0, v4, 4, 2
	s_lshl_b32 s6, s6, 1
	v_ashrrev_i32_e32 v1, 6, v4
	v_bitop3_b32 v0, v0, v4, 3 bitop3:0x78
	s_add_u32 s24, s50, s6
	v_lshlrev_b32_e32 v2, 3, v0
	v_lshlrev_b32_e32 v0, 15, v1
	v_lshlrev_b32_e32 v3, 9, v4
	v_lshlrev_b32_e32 v5, 16, v1
	v_lshlrev_b32_e32 v1, 10, v1
	s_addc_u32 s25, s51, 0
	v_and_b32_e32 v3, 0x7800, v3
	v_add_u32_e32 v91, 32, v1
	s_add_u32 s60, s52, s6
	s_mov_b32 s76, s6
	v_or3_b32 v0, v3, v0, v2
	v_or3_b32 v2, v3, v5, v2
	v_add_u32_e32 v92, v91, v1
	s_addc_u32 s61, s53, 0
	v_add_u32_e32 v5, 0x1000, v92
	v_ashrrev_i32_e32 v1, 31, v0
	v_ashrrev_i32_e32 v3, 31, v2
	v_readfirstlane_b32 s6, v91
	v_lshl_add_u64 v[82:83], v[0:1], 1, s[24:25]
	v_lshl_add_u64 v[84:85], v[2:3], 1, s[60:61]
	s_add_u32 s77, s76, 0x80
	v_lshl_add_u64 v[210:211], v[2:3], 1, s[52:53]
	v_lshl_add_u64 v[212:213], v[210:211], 0, s[8:9]
	v_bfe_u32 v214, v204, 2, 4
	v_lshlrev_b32_e32 v214, 7, v214
	v_or_b32_e32 v215, 0x800, v214
	v_mov_b32_e32 v217, 0
	s_mov_b32 m0, s6
	v_readfirstlane_b32 s6, v5
	v_add_u32_e32 v2, 0x1400, v92
	global_load_lds_dwordx4 v[82:83], off
	s_mov_b32 m0, s6
	v_readfirstlane_b32 s6, v2
	v_add_u32_e32 v2, 0x3000, v91
	v_xor_b32_e32 v216, s76, v214
	v_lshl_add_u64 v[0:1], v[210:211], 0, v[216:217]
	global_load_lds_dwordx4 v[0:1], off
	v_xor_b32_e32 v216, s76, v215
	v_lshl_add_u64 v[0:1], v[212:213], 0, v[216:217]
	s_mov_b32 m0, s6
	v_readfirstlane_b32 s6, v2
	v_add_u32_e32 v2, 0x4000, v92
	global_load_lds_dwordx4 v[0:1], off
	v_lshl_add_u64 v[0:1], v[82:83], 0, 64
	s_mov_b32 m0, s6
	v_readfirstlane_b32 s6, v2
	v_add_u32_e32 v2, 0x4400, v92
	global_load_lds_dwordx4 v[0:1], off
	v_xor_b32_e32 v216, s76, v214
	v_add_u32_e32 v216, 64, v216
	v_lshl_add_u64 v[0:1], v[210:211], 0, v[216:217]
	s_mov_b32 m0, s6
	v_readfirstlane_b32 s6, v2
	v_add_u32_e32 v2, 0x6000, v91
	global_load_lds_dwordx4 v[0:1], off
	v_xor_b32_e32 v216, s76, v215
	v_add_u32_e32 v216, 64, v216
	v_lshl_add_u64 v[0:1], v[212:213], 0, v[216:217]
	s_mov_b32 m0, s6
	v_readfirstlane_b32 s6, v2
	v_add_u32_e32 v2, 0x7000, v92
	global_load_lds_dwordx4 v[0:1], off
	v_lshl_add_u64 v[0:1], v[82:83], 0, s[12:13]
	s_mov_b32 m0, s6
	v_readfirstlane_b32 s6, v2
	v_add_u32_e32 v2, 0x7400, v92
	global_load_lds_dwordx4 v[0:1], off
	v_xor_b32_e32 v216, s77, v214
	v_lshl_add_u64 v[0:1], v[210:211], 0, v[216:217]
	s_mov_b32 m0, s6
	v_readfirstlane_b32 s6, v2
	global_load_lds_dwordx4 v[0:1], off
	v_xor_b32_e32 v216, s77, v215
	v_lshl_add_u64 v[0:1], v[212:213], 0, v[216:217]
	s_mov_b32 m0, s6
	v_lshrrev_b32_e32 v2, 2, v4
	global_load_lds_dwordx4 v[0:1], off
	v_and_b32_e32 v0, 31, v4
	v_and_or_b32 v0, v2, s41, v0
	v_bfe_u32 v1, v4, 5, 1
	v_lshlrev_b32_e32 v93, 6, v0
	v_lshlrev_b32_e32 v0, 6, v4
	v_bfe_u32 v3, v4, 2, 2
	v_and_b32_e32 v94, 0x17c0, v0
	v_bitop3_b32 v0, v1, v2, 3 bitop3:0x78
	v_lshlrev_b32_e32 v95, 4, v0
	v_bitop3_b32 v0, v1, v3, 2 bitop3:0x36
	s_mov_b32 s21, s7
	s_mov_b32 s55, 3
	v_lshlrev_b32_e32 v96, 4, v0
	s_add_i32 s60, s54, -1
	s_movk_i32 s6, 0x60
	s_mov_b32 s61, 0
	v_mov_b32_e32 v16, 0
	v_mov_b32_e32 v17, v86
	v_mov_b32_e32 v18, v86
	v_mov_b32_e32 v19, v86
	v_mov_b32_e32 v20, v86
	v_mov_b32_e32 v21, v86
	v_mov_b32_e32 v22, v86
	v_mov_b32_e32 v23, v86
	v_mov_b32_e32 v24, v86
	v_mov_b32_e32 v25, v86
	v_mov_b32_e32 v26, v86
	v_mov_b32_e32 v27, v86
	v_mov_b32_e32 v28, v86
	v_mov_b32_e32 v29, v86
	v_mov_b32_e32 v30, v86
	v_mov_b32_e32 v31, v86
	v_mov_b32_e32 v0, 0
	v_mov_b32_e32 v1, v86
	v_mov_b32_e32 v2, v86
	v_mov_b32_e32 v3, v86
	v_mov_b32_e32 v4, v86
	v_mov_b32_e32 v5, v86
	v_mov_b32_e32 v6, v86
	v_mov_b32_e32 v7, v86
	v_mov_b32_e32 v8, v86
	v_mov_b32_e32 v9, v86
	v_mov_b32_e32 v10, v86
	v_mov_b32_e32 v11, v86
	v_mov_b32_e32 v12, v86
	v_mov_b32_e32 v13, v86
	v_mov_b32_e32 v14, v86
	v_mov_b32_e32 v15, v86
	s_branch .LBB0_646

.LBB0_656:
	s_andn2_b64 vcc, exec, s[24:25]
	s_cbranch_vccnz .LBB0_645
	s_mul_i32 s64, s61, 0x3000
	s_lshl_b64 s[24:25], s[6:7], 1
	s_and_b32 s78, s24, 0xffffff80
	s_add_u32 s78, s78, s76
	s_and_b32 s79, s24, 64
	s_add_i32 s65, s64, 0xffffd000
	s_cmp_lg_u32 s61, 0
	s_cselect_b32 s65, s65, 0x9000
	v_add_u32_e32 v97, s65, v91
	v_lshl_add_u64 v[98:99], v[82:83], 0, s[24:25]
	v_readfirstlane_b32 s66, v97
	v_add_u32_e32 v97, s65, v92
	s_mov_b32 m0, s66
	v_add_u32_e32 v100, 0x1000, v97
	global_load_lds_dwordx4 v[98:99], off
	v_xor_b32_e32 v216, s78, v214
	v_add_u32_e32 v216, s79, v216
	v_lshl_add_u64 v[98:99], v[210:211], 0, v[216:217]
	v_readfirstlane_b32 s24, v100
	v_add_u32_e32 v97, 0x1400, v97
	s_mov_b32 m0, s24
	v_readfirstlane_b32 s24, v97
	global_load_lds_dwordx4 v[98:99], off
	v_xor_b32_e32 v216, s78, v215
	v_add_u32_e32 v216, s79, v216
	v_lshl_add_u64 v[98:99], v[212:213], 0, v[216:217]
	s_mov_b32 m0, s24
	s_nop 0
	global_load_lds_dwordx4 v[98:99], off
	s_branch .LBB0_645
